# same code as the previous version, shifted by 64 bytes (16 s_nop at entry): code placement changes the timing by a few hundredths of a ms
# baseline (speedup 1.0000x reference)
_Z3fwd4Args:
	s_nop 0
	s_nop 0
	s_nop 0
	s_nop 0
	s_nop 0
	s_nop 0
	s_nop 0
	s_nop 0
	s_nop 0
	s_nop 0
	s_nop 0
	s_nop 0
	s_nop 0
	s_nop 0
	s_nop 0
	s_nop 0
	v_readfirstlane_b32 s76, v0
	s_lshr_b32 s75, s76, 6
	s_add_u32 s4, s0, 0xe8
	s_addc_u32 s5, s1, 0
	s_mov_b32 s80, s2
	v_writelane_b32 v251, s4, 0
	s_and_b32 s2, s76, 0xffffffc0
	s_nop 0
	v_writelane_b32 v251, s5, 1
	v_writelane_b32 v251, s0, 2
	s_load_dword s78, s[0:1], 0xe8
	s_nop 0
	v_writelane_b32 v251, s1, 3
	s_mov_b32 s0, -1
	s_nop 0
	v_mbcnt_lo_u32_b32 v0, s0, 0
	v_mbcnt_hi_u32_b32 v1, s0, v0
	v_add_u32_e32 v0, s2, v1
	s_movk_i32 s0, 0x1000
	v_cmp_gt_i32_e32 vcc, s0, v0
	s_and_saveexec_b64 s[0:1], vcc
	s_cbranch_execz .LBB0_3
	s_lshl_b32 s4, s75, 8
	s_add_i32 s4, s4, 0
	v_lshl_add_u32 v1, v1, 2, s4
	v_add_u32_e32 v0, 0xfffffe00, v0
	v_add_u32_e32 v1, 0x20000, v1
	s_mov_b64 s[4:5], 0
	v_mov_b32_e32 v2, 0
	s_movk_i32 s6, 0xdff
